# retention matrix-core loop: staging / previous-block output VALU+LDS work interleaved into the MFMA shadows (3 per MFMA)
# baseline (speedup 1.0000x reference)
.Lgla_loop_ret:
	ds_read_b128 v[20:23], v56 offset:16384
	ds_read_b128 v[24:27], v56 offset:8192
	ds_read_b32 v28, v57 offset:8192
	ds_read_b32 v29, v57 offset:10240
	ds_read_b32 v30, v57 offset:12288
	ds_read_b32 v31, v57 offset:14336
	ds_read_b64 v[32:33], v58 offset:24576
	ds_read_b64 v[34:35], v58 offset:25088
	ds_read_b64 v[36:37], v58 offset:25600
	ds_read_b64 v[38:39], v58 offset:26112
	ds_read2_b32 v[104:105], v150 offset0:0 offset1:32
	ds_read2_b32 v[106:107], v150 offset0:64 offset1:96
	ds_read2_b32 v[108:109], v150 offset0:128 offset1:160
	ds_read2_b32 v[110:111], v150 offset0:192 offset1:224
	s_waitcnt lgkmcnt(12)
	v_pk_mul_f32 v[20:21], v[20:21], v[40:41]
	v_pk_mul_f32 v[22:23], v[22:23], v[40:41]
	s_nop 1
	v_mfma_f32_16x16x4_f32 v[16:19], v24, v20, 0
	s_waitcnt vmcnt(7)
	v_lshlrev_b32_e32 v180, 16, v190
	v_and_b32_e32 v181, s69, v190
	v_mfma_f32_16x16x4_f32 v[8:11], v0, v20, 0
	v_lshlrev_b32_e32 v182, 16, v191
	v_and_b32_e32 v183, s69, v191
	v_lshlrev_b32_e32 v184, 16, v126
	v_mfma_f32_16x16x4_f32 v[16:19], v25, v21, v[16:19]
	v_and_b32_e32 v185, s69, v126
	v_lshlrev_b32_e32 v186, 16, v127
	v_and_b32_e32 v187, s69, v127
	v_mfma_f32_16x16x4_f32 v[12:15], v4, v20, 0
	v_lshlrev_b32_e32 v188, 16, v119
	v_and_b32_e32 v189, s69, v119
	ds_write_b128 v139, v[180:183] offset:40960
	v_mfma_f32_16x16x4_f32 v[16:19], v26, v22, v[16:19]
	ds_write_b128 v139, v[184:187] offset:49152
	ds_write2_b32 v153, v188, v189 offset1:4
	global_load_dwordx2 v[126:127], v130, s[8:9]
	v_mfma_f32_16x16x4_f32 v[8:11], v1, v21, v[8:11]
	global_load_dwordx2 v[190:191], v130, s[8:9] offset:1024
	global_load_dword v119, v131, s[8:9]
	s_add_u32 s8, s8, 0x34000
	s_addc_u32 s9, s9, 0
	s_waitcnt lgkmcnt(3)
	v_mfma_f32_16x16x4_f32 v[16:19], v27, v23, v[16:19]
	v_add_f32_e32 v112, v104, v105
	v_add_f32_e32 v112, v112, v106
	v_add_f32_e32 v112, v112, v107
	v_mfma_f32_16x16x4_f32 v[12:15], v5, v21, v[12:15]
	v_add_f32_e32 v112, v112, v108
	v_add_f32_e32 v112, v112, v109
	v_add_f32_e32 v112, v112, v110
	v_mfma_f32_16x16x4_f32 v[8:11], v2, v22, v[8:11]
	v_add_f32_e32 v112, v112, v111
	v_mul_f32_e32 v113, v112, v112
	v_cvt_pk_bf16_f32 v116, v112, v129
	v_mfma_f32_16x16x4_f32 v[12:15], v6, v22, v[12:15]
	v_mov_b32_e32 v117, v112
	v_mov_b32_e32 v118, v113
	global_store_short v132, v116, s[10:11]
	v_mfma_f32_16x16x4_f32 v[8:11], v3, v23, v[8:11]
	s_nop 1
	v_permlane16_swap_b32_e32 v112, v117
	v_permlane16_swap_b32_e32 v113, v118
	v_add_f32_e32 v112, v112, v117
	v_mfma_f32_16x16x4_f32 v[12:15], v7, v23, v[12:15]
	v_add_f32_e32 v113, v113, v118
	s_nop 1
	v_add_f32_dpp v112, v112, v112 row_ror:8 row_mask:0xf bank_mask:0xf
	v_add_f32_dpp v113, v113, v113 row_ror:8 row_mask:0xf bank_mask:0xf
	s_waitcnt lgkmcnt(7)
	v_mul_f32_e32 v28, v28, v44
	v_mul_f32_e32 v29, v29, v45
	v_mul_f32_e32 v30, v30, v46
	v_mul_f32_e32 v31, v31, v47
	v_pk_mul_f32 v[0:1], v[0:1], v[52:53]
	v_pk_mul_f32 v[2:3], v[2:3], v[52:53]
	v_pk_mul_f32 v[4:5], v[4:5], v[52:53]
	v_pk_mul_f32 v[6:7], v[6:7], v[52:53]
	v_pk_mul_f32 v[16:17], v[16:17], v[48:49]
	v_pk_mul_f32 v[18:19], v[18:19], v[50:51]
	s_nop 1
	v_permlane16_swap_b32_e32 v16, v17
	v_permlane16_swap_b32_e32 v18, v19
	s_nop 1
	v_permlane32_swap_b32_e32 v16, v18
	v_permlane32_swap_b32_e32 v17, v19
	s_nop 1
	v_mfma_f32_16x16x4_f32 v[8:11], v32, v16, v[8:11]
	s_nop 1
	v_add_f32_dpp v112, v112, v112 row_ror:4 row_mask:0xf bank_mask:0xf
	v_add_f32_dpp v113, v113, v113 row_ror:4 row_mask:0xf bank_mask:0xf
	s_nop 1
	v_add_f32_dpp v112, v112, v112 row_ror:2 row_mask:0xf bank_mask:0xf
	v_mfma_f32_16x16x4_f32 v[12:15], v33, v16, v[12:15]
	v_add_f32_dpp v113, v113, v113 row_ror:2 row_mask:0xf bank_mask:0xf
	s_nop 1
	v_add_f32_dpp v112, v112, v112 row_ror:1 row_mask:0xf bank_mask:0xf
	v_add_f32_dpp v113, v113, v113 row_ror:1 row_mask:0xf bank_mask:0xf
	v_mfma_f32_16x16x4_f32 v[8:11], v34, v17, v[8:11]
	v_mov_b32_e32 v114, 0
	v_mov_b32_e32 v115, 0
	s_nop 0
	s_mov_b64 exec, s[18:19]
	global_store_dwordx4 v133, v[112:115], s[12:13]
	s_mov_b64 exec, -1
	s_cmp_eq_u32 s15, 512
	s_cselect_b32 s20, 0, 0x10000
	s_cselect_b32 s21, 0, 0x1000
	s_add_u32 s10, s10, s20
	s_addc_u32 s11, s11, 0
	s_add_u32 s12, s12, s21
	s_addc_u32 s13, s13, 0
	v_mfma_f32_16x16x4_f32 v[12:15], v35, v17, v[12:15]
	v_mfma_f32_16x16x4_f32 v[8:11], v36, v18, v[8:11]
	v_mfma_f32_16x16x4_f32 v[12:15], v37, v18, v[12:15]
	v_mfma_f32_16x16x4_f32 v[8:11], v38, v19, v[8:11]
	v_mfma_f32_16x16x4_f32 v[12:15], v39, v19, v[12:15]
	v_mfma_f32_16x16x4_f32 v[0:3], v28, v32, v[0:3]
	v_mfma_f32_16x16x4_f32 v[4:7], v28, v33, v[4:7]
	v_mfma_f32_16x16x4_f32 v[0:3], v29, v34, v[0:3]
	v_mfma_f32_16x16x4_f32 v[4:7], v29, v35, v[4:7]
	v_mfma_f32_16x16x4_f32 v[0:3], v30, v36, v[0:3]
	v_mfma_f32_16x16x4_f32 v[4:7], v30, v37, v[4:7]
	v_mfma_f32_16x16x4_f32 v[0:3], v31, v38, v[0:3]
	v_mfma_f32_16x16x4_f32 v[4:7], v31, v39, v[4:7]
	s_nop 1
	ds_write_b128 v59, v[8:11]
	ds_write_b128 v59, v[12:15] offset:64
	s_sub_u32 s15, s15, 1
	s_waitcnt lgkmcnt(0)
	s_barrier
	ds_read_b128 v[20:23], v56 offset:49152
	ds_read_b128 v[24:27], v56 offset:40960
	ds_read_b32 v28, v57 offset:40960
	ds_read_b32 v29, v57 offset:43008
	ds_read_b32 v30, v57 offset:45056
	ds_read_b32 v31, v57 offset:47104
	ds_read_b64 v[32:33], v58 offset:57344
	ds_read_b64 v[34:35], v58 offset:57856
	ds_read_b64 v[36:37], v58 offset:58368
	ds_read_b64 v[38:39], v58 offset:58880
	ds_read2_b32 v[104:105], v149 offset0:0 offset1:32
	ds_read2_b32 v[106:107], v149 offset0:64 offset1:96
	ds_read2_b32 v[108:109], v149 offset0:128 offset1:160
	ds_read2_b32 v[110:111], v149 offset0:192 offset1:224
	s_waitcnt lgkmcnt(12)
	v_pk_mul_f32 v[20:21], v[20:21], v[40:41]
	v_pk_mul_f32 v[22:23], v[22:23], v[40:41]
	s_nop 1
	v_mfma_f32_16x16x4_f32 v[16:19], v24, v20, 0
	s_waitcnt vmcnt(7)
	v_lshlrev_b32_e32 v180, 16, v122
	v_and_b32_e32 v181, s69, v122
	v_mfma_f32_16x16x4_f32 v[8:11], v0, v20, 0
	v_lshlrev_b32_e32 v182, 16, v123
	v_and_b32_e32 v183, s69, v123
	v_lshlrev_b32_e32 v184, 16, v120
	v_mfma_f32_16x16x4_f32 v[16:19], v25, v21, v[16:19]
	v_and_b32_e32 v185, s69, v120
	v_lshlrev_b32_e32 v186, 16, v121
	v_and_b32_e32 v187, s69, v121
	v_mfma_f32_16x16x4_f32 v[12:15], v4, v20, 0
	v_lshlrev_b32_e32 v188, 16, v124
	v_and_b32_e32 v189, s69, v124
	ds_write_b128 v139, v[180:183] offset:8192
	v_mfma_f32_16x16x4_f32 v[16:19], v26, v22, v[16:19]
	ds_write_b128 v139, v[184:187] offset:16384
	ds_write2_b32 v140, v188, v189 offset1:4
	global_load_dwordx2 v[120:121], v130, s[8:9]
	v_mfma_f32_16x16x4_f32 v[8:11], v1, v21, v[8:11]
	global_load_dwordx2 v[122:123], v130, s[8:9] offset:1024
	global_load_dword v124, v131, s[8:9]
	s_add_u32 s8, s8, 0x34000
	s_addc_u32 s9, s9, 0
	s_waitcnt lgkmcnt(3)
	v_mfma_f32_16x16x4_f32 v[16:19], v27, v23, v[16:19]
	v_add_f32_e32 v112, v104, v105
	v_add_f32_e32 v112, v112, v106
	v_add_f32_e32 v112, v112, v107
	v_mfma_f32_16x16x4_f32 v[12:15], v5, v21, v[12:15]
	v_add_f32_e32 v112, v112, v108
	v_add_f32_e32 v112, v112, v109
	v_add_f32_e32 v112, v112, v110
	v_mfma_f32_16x16x4_f32 v[8:11], v2, v22, v[8:11]
	v_add_f32_e32 v112, v112, v111
	v_mul_f32_e32 v113, v112, v112
	v_cvt_pk_bf16_f32 v116, v112, v129
	v_mfma_f32_16x16x4_f32 v[12:15], v6, v22, v[12:15]
	v_mov_b32_e32 v117, v112
	v_mov_b32_e32 v118, v113
	global_store_short v132, v116, s[10:11]
	v_mfma_f32_16x16x4_f32 v[8:11], v3, v23, v[8:11]
	s_nop 1
	v_permlane16_swap_b32_e32 v112, v117
	v_permlane16_swap_b32_e32 v113, v118
	v_add_f32_e32 v112, v112, v117
	v_mfma_f32_16x16x4_f32 v[12:15], v7, v23, v[12:15]
	v_add_f32_e32 v113, v113, v118
	s_nop 1
	v_add_f32_dpp v112, v112, v112 row_ror:8 row_mask:0xf bank_mask:0xf
	v_add_f32_dpp v113, v113, v113 row_ror:8 row_mask:0xf bank_mask:0xf
	s_waitcnt lgkmcnt(7)
	v_mul_f32_e32 v28, v28, v44
	v_mul_f32_e32 v29, v29, v45
	v_mul_f32_e32 v30, v30, v46
	v_mul_f32_e32 v31, v31, v47
	v_pk_mul_f32 v[0:1], v[0:1], v[52:53]
	v_pk_mul_f32 v[2:3], v[2:3], v[52:53]
	v_pk_mul_f32 v[4:5], v[4:5], v[52:53]
	v_pk_mul_f32 v[6:7], v[6:7], v[52:53]
	v_pk_mul_f32 v[16:17], v[16:17], v[48:49]
	v_pk_mul_f32 v[18:19], v[18:19], v[50:51]
	s_nop 1
	v_permlane16_swap_b32_e32 v16, v17
	v_permlane16_swap_b32_e32 v18, v19
	s_nop 1
	v_permlane32_swap_b32_e32 v16, v18
	v_permlane32_swap_b32_e32 v17, v19
	s_nop 1
	v_mfma_f32_16x16x4_f32 v[8:11], v32, v16, v[8:11]
	s_nop 1
	v_add_f32_dpp v112, v112, v112 row_ror:4 row_mask:0xf bank_mask:0xf
	v_add_f32_dpp v113, v113, v113 row_ror:4 row_mask:0xf bank_mask:0xf
	s_nop 1
	v_add_f32_dpp v112, v112, v112 row_ror:2 row_mask:0xf bank_mask:0xf
	v_mfma_f32_16x16x4_f32 v[12:15], v33, v16, v[12:15]
	v_add_f32_dpp v113, v113, v113 row_ror:2 row_mask:0xf bank_mask:0xf
	s_nop 1
	v_add_f32_dpp v112, v112, v112 row_ror:1 row_mask:0xf bank_mask:0xf
	v_add_f32_dpp v113, v113, v113 row_ror:1 row_mask:0xf bank_mask:0xf
	v_mfma_f32_16x16x4_f32 v[8:11], v34, v17, v[8:11]
	v_mov_b32_e32 v114, 0
	v_mov_b32_e32 v115, 0
	s_nop 0
	s_mov_b64 exec, s[18:19]
	global_store_dwordx4 v133, v[112:115], s[12:13]
	s_mov_b64 exec, -1
	s_cmp_eq_u32 s15, 512
	s_cselect_b32 s20, 0, 0x10000
	s_cselect_b32 s21, 0, 0x1000
	s_add_u32 s10, s10, s20
	s_addc_u32 s11, s11, 0
	s_add_u32 s12, s12, s21
	s_addc_u32 s13, s13, 0
	v_mfma_f32_16x16x4_f32 v[12:15], v35, v17, v[12:15]
	v_mfma_f32_16x16x4_f32 v[8:11], v36, v18, v[8:11]
	v_mfma_f32_16x16x4_f32 v[12:15], v37, v18, v[12:15]
	v_mfma_f32_16x16x4_f32 v[8:11], v38, v19, v[8:11]
	v_mfma_f32_16x16x4_f32 v[12:15], v39, v19, v[12:15]
	v_mfma_f32_16x16x4_f32 v[0:3], v28, v32, v[0:3]
	v_mfma_f32_16x16x4_f32 v[4:7], v28, v33, v[4:7]
	v_mfma_f32_16x16x4_f32 v[0:3], v29, v34, v[0:3]
	v_mfma_f32_16x16x4_f32 v[4:7], v29, v35, v[4:7]
	v_mfma_f32_16x16x4_f32 v[0:3], v30, v36, v[0:3]
	v_mfma_f32_16x16x4_f32 v[4:7], v30, v37, v[4:7]
	v_mfma_f32_16x16x4_f32 v[0:3], v31, v38, v[0:3]
	v_mfma_f32_16x16x4_f32 v[4:7], v31, v39, v[4:7]
	s_nop 1
	ds_write_b128 v60, v[8:11]
	ds_write_b128 v60, v[12:15] offset:64
	s_sub_u32 s15, s15, 1
	s_waitcnt lgkmcnt(0)
	s_barrier
	s_cmp_lg_u32 s15, 0
	s_cbranch_scc1 .Lgla_loop_ret
